# cross-attention items remapped so the 8 waves of a workgroup share one (batch, head): K/V tile loads hit the CU L1
# speedup vs baseline: 1.0018x; 1.0018x over previous
; #define LAS __attribute__((address_space(3)))
; __device__ __forceinline__ void xattn_mfma_item(const bf16* qx, const bf16* kv, bf16* ox, LAS unsigned char* wl, int item, int lane) {
;     const int head = item & 3, qblk = item >> 2;
;     const int r = lane & 31, hi = lane >> 5;
;     const int token = qblk * 32 + r, b = (qblk * 32) / S;
;     s16x8 Qf[8];
;     { const char* qb_ = (const char*)qx; const unsigned qo = (unsigned)(token * DX + head * 128 + 8 * hi) * 2u;
; #pragma unroll
;       for (int d0 = 0; d0 < 8; ++d0) Qf[d0] = *(const s16x8*)(qb_ + qo + 32 * d0); }
;     f32x16 O[4];
; #pragma unroll
;     for (int k = 0; k < 4; ++k)
; #pragma unroll
;         for (int i = 0; i < 16; ++i) O[k][i] = 0.f;
;     float mrun = -1e30f, lsum = 0.f;
;     const int trbase = (4 * hi + ((lane >> 2) & 3)) * PV128 + (16 * ((lane >> 4) & 1) + 4 * (lane & 3)) * 2;
;     const char* kvc = (const char*)(kv + (size_t)b * MEML * 1024);
;     const unsigned kfo = (unsigned)(r * 1024 + head * 128 + 8 * hi) * 2u;
;     const unsigned vlo = (unsigned)((lane >> 4) * 1024 + 512 + head * 128 + 8 * (lane & 15)) * 2u;
; __global__ void __launch_bounds__(512, 2) mega_fwd(Args a) {
;     ...
;             for (int it = gw; it < 2048; it += NGW) xattn_mfma_item(qxb, kvb + (size_t)l * MROWS * 1024, oxb, L + wave * 16384, it, lane);
.LBB0_584:
	s_and_b64 vcc, exec, s[18:19]
	s_cbranch_vccz .LBB0_620
	s_add_u32 s2, s80, 0xac00000
	s_addc_u32 s3, s81, 0
	v_writelane_b32 v253, s2, 47
	v_and_b32_e32 v202, 63, v1
	s_nop 0
	v_writelane_b32 v253, s3, 48
	s_add_u32 s2, s80, 0xf000000
	s_addc_u32 s3, s81, 0
	v_writelane_b32 v253, s2, 49
	s_nop 1
	v_writelane_b32 v253, s3, 50
	s_ashr_i32 s2, s41, 6
	v_writelane_b32 v253, s2, 51
	s_cmp_gt_i32 s38, 1
	s_cbranch_scc0 .LBB0_596
	s_cmp_gt_i32 s38, 3
	s_mov_b64 s[2:3], -1
	s_cbranch_scc0 .LBB0_614
	v_readlane_b32 s2, v253, 10
	v_readlane_b32 s3, v253, 51
	s_add_i32 s10, s3, s2
	s_cmpk_gt_i32 s10, 0x7ff
	s_cbranch_scc1 .LBB0_613
	s_lshr_b32 s2, s10, 5
	s_lshl_b32 s2, s2, 3
	s_and_b32 s3, s10, 7
	s_add_i32 s2, s2, s3
	s_lshl_b32 s2, s2, 2
	s_bfe_u32 s3, s10, 0x20003
	s_or_b32 s10, s2, s3
	s_lshl_b64 s[2:3], s[78:79], 19
	s_and_b32 s2, s2, 0xffc00000
	s_lshl_b64 s[14:15], s[0:1], 22
	v_readlane_b32 s16, v253, 49
	v_readlane_b32 s17, v253, 50
	s_add_u32 s1, s16, s14
	s_addc_u32 s11, s17, s15
	v_readlane_b32 s15, v253, 51
	s_lshl_b32 s14, s15, 14
	s_add_i32 s14, s14, 0
	v_and_b32_e32 v5, 16, v1
	v_lshlrev_b32_e32 v6, 2, v202
	v_lshrrev_b32_e32 v2, 5, v202
	v_and_or_b32 v5, v6, 12, v5
	v_and_b32_e32 v6, 15, v1
	s_add_u32 s2, s12, s2
	v_lshlrev_b32_e32 v219, 3, v2
	v_lshlrev_b32_e32 v220, 2, v2
	v_lshrrev_b32_e32 v2, 2, v1
	v_lshrrev_b32_e32 v4, 4, v202
	v_lshlrev_b32_e32 v7, 3, v6
	s_addc_u32 s3, s13, s3
	v_and_or_b32 v2, v2, 3, v220
	v_lshl_or_b32 v222, v4, 10, v7
	v_mov_b32_e32 v7, s14
	s_movk_i32 s14, 0x110
	s_add_u32 s12, s62, s2
	v_mad_u32_u24 v4, v4, s14, v7
	v_mad_u32_u24 v2, v2, s14, v7
	s_addc_u32 s13, s63, s3
	s_lshl_b32 s14, s15, 7
	v_readlane_b32 s15, v253, 36
	s_lshl_b32 s14, s10, 7
	v_readlane_b32 s15, v253, 38
	v_and_b32_e32 v203, 31, v1
	v_lshlrev_b32_e32 v5, 1, v5
	v_lshlrev_b32_e32 v6, 4, v6
	s_add_u32 s15, s15, s2
	v_readlane_b32 s2, v253, 39
	v_lshl_or_b32 v221, v203, 10, v219
	s_addc_u32 s16, s2, s3
	v_add_u32_e32 v223, v4, v6
	v_add_u32_e32 v224, v2, v5
	s_branch .LBB0_590
